# v17 plus SSD conv main-row loads hoisted above the dt/cumsum step and its barrier
# speedup vs baseline: 1.0034x; 1.0022x over previous
; __device__ __forceinline__ float fexp2(float x) { return __builtin_amdgcn_exp2f(x); }
; __device__ __forceinline__ void ssd_phase(const Frame& F, const Args& a, int z, int li, bf16* PROJ, const float* DT, bf16* dryXB) {
;     ...
;             if (tid < 256) {
;                 const int hr = g * 4 + wave;
;                 const float raw = dt_pf + dtb_i;
;                 const float dt = raw > 20.f ? raw : log1pf(__expf(raw));
;                 const float am = am_i;
;                 float v = dt * am;
; #pragma unroll
;                 for (int o = 1; o < 64; o <<= 1) { const float n = __shfl_up(v, o); if (lane >= o) v += n; }
;                 const float last = __shfl(v, 63);
;                 dts[wave * 64 + lane] = dt; cums[wave * 64 + lane] = v; wins[wave * 64 + lane] = fexp2(last - v) * dt;
;             }
;             __syncthreads();
;             {
;                 const bf16* src = PROJ + 2048 + chbase;
;                 u32x4 raw[11];
; #pragma unroll
;                 for (int i = 0; i < 11; ++i) {
;                     const int rr = 8 * wave - 3 + i;
;                     if (rr >= 0 || c > 0) raw[i] = *(const u32x4*)(src + (size_t)((long)rowc + rr) * LDP);
.LBB0_414:
	s_andn2_saveexec_b64 s[6:7], s[6:7]
	v_add_u32_e32 v110, s5, v209
	s_or_b64 exec, exec, s[6:7]
	v_ashrrev_i32_e32 v111, 31, v110
	v_lshl_add_u64 v[224:225], v[110:111], 1, s[30:31]
	s_add_i32 s16, s50, s54
	v_mad_u64_u32 v[78:79], s[14:15], s16, v229, v[224:225]
	s_add_i32 s14, s50, s78
	s_nop 0
	v_mad_u64_u32 v[80:81], s[14:15], s14, v229, v[224:225]
	s_add_i32 s14, s16, 4
	s_nop 0
	v_mad_u64_u32 v[86:87], s[14:15], s14, v229, v[224:225]
	s_add_i32 s14, s16, 5
	s_nop 0
	v_mad_u64_u32 v[88:89], s[14:15], s14, v229, v[224:225]
	s_add_i32 s14, s16, 6
	s_nop 0
	v_mad_u64_u32 v[90:91], s[14:15], s14, v229, v[224:225]
	s_add_i32 s14, s16, 7
	s_add_i32 s17, s50, s85
	v_mad_u64_u32 v[94:95], s[14:15], s14, v229, v[224:225]
	s_add_i32 s16, s16, 3
	global_load_dwordx4 v[82:85], v[78:79], off
	s_nop 0
	global_load_dwordx4 v[78:81], v[80:81], off
	s_nop 0
	global_load_dwordx4 v[90:93], v[90:91], off
	s_nop 0
	global_load_dwordx4 v[98:101], v[94:95], off
	s_nop 0
	global_load_dwordx4 v[94:97], v[86:87], off
	s_nop 0
	global_load_dwordx4 v[86:89], v[88:89], off
	v_mad_u64_u32 v[104:105], s[14:15], s17, v229, v[224:225]
	v_mad_u64_u32 v[102:103], s[14:15], s16, v229, v[224:225]
	global_load_dwordx4 v[106:109], v[104:105], off
	s_nop 0
	global_load_dwordx4 v[102:105], v[102:103], off
	v_add_u32_e32 v0, s73, v168
	s_movk_i32 s6, 0x100
	v_cmp_gt_i32_e64 s[6:7], s6, v0
	s_and_saveexec_b64 s[14:15], s[6:7]
	s_cbranch_execz .LBB0_420
	v_add_f32_e32 v234, v207, v169
	s_mov_b32 s16, 0x41a00000
	v_cmp_nlt_f32_e32 vcc, s16, v234
	s_and_saveexec_b64 s[16:17], vcc
	s_cbranch_execz .LBB0_419
	v_mul_f32_e32 v234, 0x3fb8aa3b, v234
	v_exp_f32_e32 v250, v234
	s_mov_b32 s44, 0x3f2aaaab
	v_add_f32_e32 v236, 1.0, v250
	v_frexp_mant_f32_e32 v240, v236
	v_cvt_f64_f32_e32 v[234:235], v236
	v_frexp_exp_i32_f64_e32 v234, v[234:235]
	v_cmp_gt_f32_e32 vcc, s44, v240
	v_add_f32_e32 v237, -1.0, v236
	v_sub_f32_e32 v241, v237, v236
	v_subbrev_co_u32_e32 v244, vcc, 0, v234, vcc
	v_sub_u32_e32 v234, 0, v244
	v_sub_f32_e32 v237, v250, v237
	v_add_f32_e32 v241, 1.0, v241
	v_ldexp_f32 v235, v236, v234
	v_add_f32_e32 v237, v237, v241
	v_add_f32_e32 v236, -1.0, v235
	v_add_f32_e32 v240, 1.0, v235
	v_ldexp_f32 v234, v237, v234
	v_add_f32_e32 v237, 1.0, v236
	v_add_f32_e32 v241, -1.0, v240
	v_sub_f32_e32 v237, v235, v237
	v_sub_f32_e32 v235, v235, v241
	v_add_f32_e32 v237, v234, v237
	v_add_f32_e32 v234, v234, v235
	v_add_f32_e32 v245, v240, v234
	v_rcp_f32_e32 v247, v245
	v_sub_f32_e32 v235, v245, v240
	v_sub_f32_e32 v246, v234, v235
	v_add_f32_e32 v235, v236, v237
	v_mul_f32_e32 v249, v235, v247
	v_sub_f32_e32 v234, v235, v236
	v_mul_f32_e32 v236, v245, v249
	v_fma_f32 v240, v249, v245, -v236
	v_fmac_f32_e32 v240, v249, v246
	v_sub_f32_e32 v248, v237, v234
	v_add_f32_e32 v234, v236, v240
	v_sub_f32_e32 v237, v235, v234
	v_pk_add_f32 v[242:243], v[234:235], v[236:237] neg_lo:[0,1] neg_hi:[0,1]
	v_mov_b32_e32 v241, v234
	v_pk_add_f32 v[234:235], v[242:243], v[240:241] neg_lo:[0,1] neg_hi:[0,1]
	s_mov_b32 s44, 0x3f317218
	v_add_f32_e32 v235, v248, v235
	v_add_f32_e32 v234, v234, v235
	v_add_f32_e32 v235, v237, v234
	v_mul_f32_e32 v248, v247, v235
	v_mul_f32_e32 v236, v245, v248
	v_fma_f32 v240, v248, v245, -v236
	v_fmac_f32_e32 v240, v248, v246
	v_sub_f32_e32 v237, v237, v235
	v_add_f32_e32 v245, v234, v237
	v_add_f32_e32 v234, v236, v240
	v_sub_f32_e32 v237, v235, v234
	v_pk_add_f32 v[242:243], v[234:235], v[236:237] neg_lo:[0,1] neg_hi:[0,1]
	v_mov_b32_e32 v241, v234
	v_pk_add_f32 v[234:235], v[242:243], v[240:241] neg_lo:[0,1] neg_hi:[0,1]
	s_nop 0
	v_add_f32_e32 v235, v245, v235
	v_add_f32_e32 v234, v234, v235
	v_add_f32_e32 v235, v249, v248
	v_add_f32_e32 v234, v237, v234
	v_sub_f32_e32 v236, v235, v249
	v_mul_f32_e32 v234, v247, v234
	v_sub_f32_e32 v236, v248, v236
	v_add_f32_e32 v236, v236, v234
	v_add_f32_e32 v240, v235, v236
	v_mul_f32_e32 v241, v240, v240
	v_mov_b32_e32 v234, 0x3ecc95a3
	v_fmamk_f32 v234, v241, 0x3e9b6dac, v234
	v_fmaak_f32 v175, v241, v234, 0x3f2aaada
	v_cvt_f32_i32_e32 v234, v244
	v_sub_f32_e32 v235, v240, v235
	v_sub_f32_e32 v235, v236, v235
	v_ldexp_f32 v242, v235, 1
	v_mul_f32_e32 v235, v240, v241
	v_ldexp_f32 v237, v240, 1
	v_pk_mul_f32 v[240:241], v[234:235], v[174:175]
	s_nop 0
	v_fma_f32 v236, v234, s44, -v240
	v_fmac_f32_e32 v236, 0xb102e308, v234
	v_pk_add_f32 v[234:235], v[240:241], v[236:237]
	s_mov_b32 s44, 0x7f800000
	v_sub_f32_e32 v237, v235, v237
	v_sub_f32_e32 v237, v241, v237
	v_add_f32_e32 v243, v242, v237
	v_mov_b32_e32 v242, v240
	v_pk_add_f32 v[240:241], v[234:235], v[240:241] neg_lo:[0,1] neg_hi:[0,1]
	v_pk_add_f32 v[244:245], v[234:235], v[242:243]
	v_mov_b32_e32 v237, v234
	v_mov_b32_e32 v241, v245
	v_pk_add_f32 v[246:247], v[236:237], v[240:241] neg_lo:[0,1] neg_hi:[0,1]
	v_pk_add_f32 v[236:237], v[236:237], v[240:241]
	v_mov_b32_e32 v242, v243
	v_pk_add_f32 v[240:241], v[236:237], v[234:235] op_sel:[1,0] op_sel_hi:[0,1] neg_lo:[0,1] neg_hi:[0,1]
	v_pk_add_f32 v[248:249], v[244:245], v[240:241] op_sel_hi:[1,0] neg_lo:[0,1] neg_hi:[0,1]
	v_mov_b32_e32 v244, v245
	v_mov_b32_e32 v245, v237
	v_pk_mov_b32 v[240:241], v[234:235], v[240:241] op_sel:[1,0]
	v_mov_b32_e32 v243, v234
	v_pk_add_f32 v[240:241], v[244:245], v[240:241] neg_lo:[0,1] neg_hi:[0,1]
	v_mov_b32_e32 v248, v246
	v_pk_add_f32 v[234:235], v[242:243], v[240:241] neg_lo:[0,1] neg_hi:[0,1]
	v_mov_b32_e32 v247, v237
	v_pk_add_f32 v[240:241], v[248:249], v[234:235]
	v_cmp_neq_f32_e32 vcc, s44, v250
	v_pk_add_f32 v[242:243], v[240:241], v[240:241] op_sel:[0,1] op_sel_hi:[1,0]
	s_mov_b32 s44, 0x33800000
	v_pk_add_f32 v[236:237], v[236:237], v[242:243] op_sel:[1,0] op_sel_hi:[0,1]
	v_mov_b32_e32 v241, v236
	v_pk_add_f32 v[244:245], v[240:241], v[246:247] neg_lo:[0,1] neg_hi:[0,1]
	v_mov_b32_e32 v235, v242
	v_sub_f32_e32 v237, v240, v244
	v_pk_add_f32 v[234:235], v[234:235], v[244:245] neg_lo:[0,1] neg_hi:[0,1]
	v_sub_f32_e32 v237, v246, v237
	v_add_f32_e32 v234, v234, v237
	v_add_f32_e32 v234, v234, v235
	v_add_f32_e32 v234, v236, v234
	v_mov_b32_e32 v235, 0x7f800000
	v_cndmask_b32_e32 v234, v235, v234, vcc
	v_cmp_ngt_f32_e32 vcc, -1.0, v250
	v_mov_b32_e32 v235, 0x7fc00000
	s_nop 0
	v_cndmask_b32_e32 v234, v235, v234, vcc
	v_cmp_neq_f32_e32 vcc, -1.0, v250
	v_mov_b32_e32 v235, 0xff800000
	s_nop 0
	v_cndmask_b32_e32 v234, v235, v234, vcc
	v_cmp_lt_f32_e64 vcc, |v250|, s44
	s_nop 1
	v_cndmask_b32_e32 v234, v234, v250, vcc
; __device__ __forceinline__ float fexp2(float x) { return __builtin_amdgcn_exp2f(x); }
; __device__ __forceinline__ void ssd_phase(const Frame& F, const Args& a, int z, int li, bf16* PROJ, const float* DT, bf16* dryXB) {
;     ...
;                 const float am = am_i;
;                 float v = dt * am;
; #pragma unroll
;                 for (int o = 1; o < 64; o <<= 1) { const float n = __shfl_up(v, o); if (lane >= o) v += n; }
;                 const float last = __shfl(v, 63);
;                 dts[wave * 64 + lane] = dt; cums[wave * 64 + lane] = v; wins[wave * 64 + lane] = fexp2(last - v) * dt;
.LBB0_419:
	s_or_b64 exec, exec, s[16:17]
	v_mul_f32_e32 v235, v208, v234
	ds_bpermute_b32 v236, v161, v235
	v_cmp_gt_i32_e32 vcc, 1, v168
	v_lshl_add_u32 v0, v0, 2, 0
	v_add_u32_e32 v237, 0x1f000, v0
	ds_write_b32 v237, v234
	s_waitcnt lgkmcnt(1)
	v_fmac_f32_e32 v236, v208, v234
	v_cndmask_b32_e32 v235, v236, v235, vcc
	ds_bpermute_b32 v236, v163, v235
	v_cmp_gt_i32_e32 vcc, 2, v168
	v_add_u32_e32 v237, 0x1f400, v0
	v_add_u32_e32 v0, 0x1f800, v0
	s_waitcnt lgkmcnt(0)
	v_add_f32_e32 v236, v235, v236
	v_cndmask_b32_e32 v235, v236, v235, vcc
	ds_bpermute_b32 v236, v185, v235
	v_cmp_gt_i32_e32 vcc, 4, v168
	s_waitcnt lgkmcnt(0)
	v_add_f32_e32 v236, v235, v236
	v_cndmask_b32_e32 v235, v236, v235, vcc
	ds_bpermute_b32 v236, v202, v235
	v_cmp_gt_i32_e32 vcc, 8, v168
	s_waitcnt lgkmcnt(0)
	v_add_f32_e32 v236, v235, v236
	v_cndmask_b32_e32 v235, v236, v235, vcc
	ds_bpermute_b32 v236, v203, v235
	v_cmp_gt_i32_e32 vcc, 16, v168
	s_waitcnt lgkmcnt(0)
	v_add_f32_e32 v236, v235, v236
	v_cndmask_b32_e32 v235, v236, v235, vcc
	ds_bpermute_b32 v236, v204, v235
	s_waitcnt lgkmcnt(0)
	v_add_f32_e32 v236, v235, v236
	v_cndmask_b32_e64 v235, v236, v235, s[12:13]
	ds_bpermute_b32 v236, v239, v235
	ds_write_b32 v237, v235
	s_waitcnt lgkmcnt(1)
	v_sub_f32_e32 v235, v236, v235
	v_exp_f32_e32 v235, v235
	s_nop 0
	v_mul_f32_e32 v234, v234, v235
	ds_write_b32 v0, v234

; __device__ __forceinline__ void ssd_phase(const Frame& F, const Args& a, int z, int li, bf16* PROJ, const float* DT, bf16* dryXB) {
;     ...
;                 for (int i = 0; i < 11; ++i) {
;                     const int rr = 8 * wave - 3 + i;
;                     if (rr >= 0 || c > 0) raw[i] = *(const u32x4*)(src + (size_t)((long)rowc + rr) * LDP);
;                     else if (!smp) raw[i] = (u32x4){0u, 0u, 0u, 0u};
.LBB0_424:
	s_andn2_b64 vcc, exec, s[16:17]
	s_cbranch_vccnz .LBB0_426
	v_readlane_b32 s16, v254, 9
	s_add_u32 s16, s50, s16
	v_readlane_b32 s17, v254, 10
	s_addc_u32 s17, 0, s17
	s_mul_i32 vcc_lo, s17, 0x3000
	v_mad_u64_u32 v[66:67], s[16:17], s16, v229, v[224:225]
	v_add_u32_e32 v67, vcc_lo, v67
	global_load_dwordx4 v[66:69], v[66:67], off

; __device__ __forceinline__ unsigned pk2(float lo, float hi) { f32x2_t v = {lo, hi}; bf16x2_t b = __builtin_convertvector(v, bf16x2_t); return __builtin_bit_cast(unsigned, b); }
; __device__ __forceinline__ void ssd_phase(const Frame& F, const Args& a, int z, int li, bf16* PROJ, const float* DT, bf16* dryXB) {
;     ...
;                 for (int i = 0; i < 11; ++i) {
;                     const int rr = 8 * wave - 3 + i;
;                     if (rr >= 0 || c > 0) raw[i] = *(const u32x4*)(src + (size_t)((long)rowc + rr) * LDP);
;                     else if (!smp) raw[i] = (u32x4){0u, 0u, 0u, 0u};
;                     else { const float* sc = AIN(5) + ((size_t)(li * 32 + b) * 3 + (3 + rr)) * 4096 + chbase; const f32x4 s0 = *(const f32x4*)sc, s1 = *(const f32x4*)(sc + 4);
;                         raw[i] = (u32x4){pk2(s0[0], s0[1]), pk2(s0[2], s0[3]), pk2(s1[0], s1[1]), pk2(s1[2], s1[3])}; }
;                 }
.LBB0_430:
	v_readlane_b32 s14, v254, 13
	s_add_u32 s14, s50, s14
	v_readlane_b32 s15, v254, 14
	s_addc_u32 s15, 0, s15
	s_mul_i32 s16, s15, 0x3000
	v_mad_u64_u32 v[74:75], s[14:15], s14, v229, v[224:225]
	v_add_u32_e32 v75, s16, v75
	global_load_dwordx4 v[74:77], v[74:75], off
.LBB0_431:
	s_cmp_eq_u32 s25, s24
	s_cselect_b64 s[16:17], -1, 0
	s_and_b64 s[16:17], s[16:17], s[52:53]
	s_mov_b64 s[14:15], -1
	s_and_b64 vcc, exec, s[16:17]
	s_waitcnt vmcnt(5)
	v_mov_b32_e32 v152, v90
	s_waitcnt vmcnt(4)
	v_mov_b32_e32 v155, v98
	v_mov_b32_e32 v153, v90
	s_waitcnt vmcnt(2)
	v_mov_b32_e32 v154, v86
	v_lshlrev_b32_e32 v130, 16, v86
	v_lshlrev_b32_e32 v131, 16, v90
	v_lshlrev_b32_e32 v129, 16, v98
	s_cbranch_vccnz .LBB0_433
	v_mov_b32_e32 v154, v86
	v_mov_b32_e32 v153, v90
	v_mov_b32_e32 v152, v90
	v_mov_b32_e32 v155, v98
	v_mov_b32_e32 v128, v131
	s_mov_b64 s[14:15], 0

; __device__ __forceinline__ unsigned pk2(float lo, float hi) { f32x2_t v = {lo, hi}; bf16x2_t b = __builtin_convertvector(v, bf16x2_t); return __builtin_bit_cast(unsigned, b); }
; __device__ __forceinline__ void ssd_phase(const Frame& F, const Args& a, int z, int li, bf16* PROJ, const float* DT, bf16* dryXB) {
;     ...
;                 for (int i = 0; i < 11; ++i) {
;                     const int rr = 8 * wave - 3 + i;
;                     if (rr >= 0 || c > 0) raw[i] = *(const u32x4*)(src + (size_t)((long)rowc + rr) * LDP);
;                     else if (!smp) raw[i] = (u32x4){0u, 0u, 0u, 0u};
;                     else { const float* sc = AIN(5) + ((size_t)(li * 32 + b) * 3 + (3 + rr)) * 4096 + chbase; const f32x4 s0 = *(const f32x4*)sc, s1 = *(const f32x4*)(sc + 4);
;                         raw[i] = (u32x4){pk2(s0[0], s0[1]), pk2(s0[2], s0[3]), pk2(s1[0], s1[1]), pk2(s1[2], s1[3])}; }
.LBB0_487:
	v_readlane_b32 s44, v254, 11
	s_add_u32 s44, s50, s44
	v_readlane_b32 s45, v254, 12
	s_addc_u32 s45, 0, s45
	s_mul_i32 vcc_lo, s45, 0x3000
	v_mad_u64_u32 v[70:71], s[44:45], s44, v229, v[224:225]
	v_add_u32_e32 v71, vcc_lo, v71
	global_load_dwordx4 v[70:73], v[70:71], off
	s_and_b64 vcc, exec, s[16:17]
	s_mov_b64 s[16:17], -1
	s_cbranch_vccnz .LBB0_429
.LBB0_488:
	v_mov_b32_e32 v77, 0
	s_and_b64 vcc, exec, s[14:15]
	v_mov_b32_e32 v76, 0
	v_mov_b32_e32 v75, 0
	v_mov_b32_e32 v74, 0
	s_cbranch_vccnz .LBB0_490
	s_load_dwordx2 s[14:15], s[88:89], 0x28
	s_waitcnt lgkmcnt(0)
	s_add_u32 s14, s14, s76
	s_addc_u32 s15, s15, s77
	v_lshl_add_u64 v[234:235], v[110:111], 2, s[14:15]
	global_load_dwordx4 v[74:77], v[234:235], off
	s_nop 0
	global_load_dwordx4 v[234:237], v[234:235], off offset:16
	s_waitcnt vmcnt(1)
	v_cvt_pk_bf16_f32 v74, v74, v75
	v_cvt_pk_bf16_f32 v75, v76, v77
	s_waitcnt vmcnt(0)
	v_cvt_pk_bf16_f32 v76, v234, v235
	v_cvt_pk_bf16_f32 v77, v236, v237
